# unneeded s_nop pads before pass-B DPP moves removed
# speedup vs baseline: 1.0039x; 1.0039x over previous
.LBB0_3846:
	s_nop 5
	v_mov_b32_dpp v54, v151 quad_perm:[1,0,3,2] row_mask:0xf bank_mask:0xf
	v_mov_b32_dpp v59, v159 quad_perm:[1,0,3,2] row_mask:0xf bank_mask:0xf
	v_mov_b32_dpp v63, v187 quad_perm:[1,0,3,2] row_mask:0xf bank_mask:0xf
	v_mov_b32_dpp v68, v195 quad_perm:[1,0,3,2] row_mask:0xf bank_mask:0xf
	v_add_f32_e32 v50, v144, v146
	s_waitcnt lgkmcnt(3)
	v_add_f32_e32 v54, v151, v54
	s_waitcnt lgkmcnt(2)
	v_add_f32_e32 v59, v159, v59
	s_waitcnt lgkmcnt(1)
	v_add_f32_e32 v63, v187, v63
	v_mov_b32_dpp v55, v54 quad_perm:[2,3,0,1] row_mask:0xf bank_mask:0xf
	v_mov_b32_dpp v60, v59 quad_perm:[2,3,0,1] row_mask:0xf bank_mask:0xf
	v_mov_b32_dpp v64, v63 quad_perm:[2,3,0,1] row_mask:0xf bank_mask:0xf
	s_waitcnt lgkmcnt(3)
	v_add_f32_e32 v68, v195, v68
	s_nop 1
	v_mov_b32_dpp v71, v68 quad_perm:[2,3,0,1] row_mask:0xf bank_mask:0xf
	s_waitcnt lgkmcnt(3)
	v_add_f32_e32 v58, v54, v55
	v_mov_b32_dpp v54, v152 quad_perm:[1,0,3,2] row_mask:0xf bank_mask:0xf
	s_waitcnt lgkmcnt(3)
	v_add_f32_e32 v69, v59, v60
	v_mov_b32_dpp v59, v162 quad_perm:[1,0,3,2] row_mask:0xf bank_mask:0xf
	s_waitcnt lgkmcnt(3)
	v_add_f32_e32 v72, v63, v64
	v_mov_b32_dpp v63, v188 quad_perm:[1,0,3,2] row_mask:0xf bank_mask:0xf
	s_waitcnt lgkmcnt(2)
	v_add_f32_e32 v54, v152, v54
	s_nop 1
	v_mov_b32_dpp v55, v54 quad_perm:[2,3,0,1] row_mask:0xf bank_mask:0xf
	s_waitcnt lgkmcnt(2)
	v_add_f32_e32 v59, v162, v59
	s_nop 1
	v_mov_b32_dpp v60, v59 quad_perm:[2,3,0,1] row_mask:0xf bank_mask:0xf
	s_waitcnt lgkmcnt(2)
	v_add_f32_e32 v63, v188, v63
	s_nop 1
	v_mov_b32_dpp v64, v63 quad_perm:[2,3,0,1] row_mask:0xf bank_mask:0xf
	v_add_f32_e32 v75, v68, v71
	v_mov_b32_dpp v68, v196 quad_perm:[1,0,3,2] row_mask:0xf bank_mask:0xf
	v_add_f32_e32 v51, v148, v151
	v_add_f32_e32 v52, v145, v147
	v_add_f32_e32 v53, v150, v152
	s_waitcnt lgkmcnt(3)
	v_add_f32_e32 v67, v54, v55
	v_add_f32_e32 v54, v153, v155
	v_add_f32_e32 v55, v157, v159
	v_add_f32_e32 v56, v154, v156
	v_add_f32_e32 v57, v158, v162
	s_waitcnt lgkmcnt(2)
	v_add_f32_e32 v70, v59, v60
	v_add_f32_e32 v59, v163, v165
	v_add_f32_e32 v60, v167, v187
	v_add_f32_e32 v61, v164, v166
	v_add_f32_e32 v62, v186, v188
	s_waitcnt lgkmcnt(1)
	v_add_f32_e32 v74, v63, v64
	v_add_f32_e32 v63, v189, v191
	v_add_f32_e32 v64, v193, v195
	v_add_f32_e32 v65, v190, v192
	v_add_f32_e32 v66, v194, v196
	v_add_f32_e32 v50, v50, v51
	v_add_f32_e32 v52, v52, v53
	v_add_f32_e32 v54, v54, v55
	v_add_f32_e32 v56, v56, v57
	v_add_f32_e32 v59, v59, v60
	v_add_f32_e32 v61, v61, v62
	v_add_f32_e32 v63, v63, v64
	v_add_f32_e32 v65, v65, v66
	s_waitcnt lgkmcnt(0)
	v_add_f32_e32 v68, v196, v68
	v_mov_b32_dpp v51, v50 quad_perm:[1,0,3,2] row_mask:0xf bank_mask:0xf
	v_mov_b32_dpp v53, v52 quad_perm:[1,0,3,2] row_mask:0xf bank_mask:0xf
	v_mov_b32_dpp v55, v54 quad_perm:[1,0,3,2] row_mask:0xf bank_mask:0xf
	v_mov_b32_dpp v57, v56 quad_perm:[1,0,3,2] row_mask:0xf bank_mask:0xf
	v_mov_b32_dpp v60, v59 quad_perm:[1,0,3,2] row_mask:0xf bank_mask:0xf
	v_mov_b32_dpp v62, v61 quad_perm:[1,0,3,2] row_mask:0xf bank_mask:0xf
	v_mov_b32_dpp v64, v63 quad_perm:[1,0,3,2] row_mask:0xf bank_mask:0xf
	v_mov_b32_dpp v66, v65 quad_perm:[1,0,3,2] row_mask:0xf bank_mask:0xf
	v_mov_b32_dpp v71, v68 quad_perm:[2,3,0,1] row_mask:0xf bank_mask:0xf
	s_waitcnt lgkmcnt(8)
	v_add_f32_e32 v50, v50, v51
	s_waitcnt lgkmcnt(7)
	v_add_f32_e32 v52, v52, v53
	s_waitcnt lgkmcnt(6)
	v_add_f32_e32 v54, v54, v55
	s_waitcnt lgkmcnt(5)
	v_add_f32_e32 v56, v56, v57
	s_waitcnt lgkmcnt(4)
	v_add_f32_e32 v59, v59, v60
	s_waitcnt lgkmcnt(3)
	v_add_f32_e32 v61, v61, v62
	s_waitcnt lgkmcnt(2)
	v_add_f32_e32 v63, v63, v64
	s_waitcnt lgkmcnt(1)
	v_add_f32_e32 v65, v65, v66
	s_waitcnt lgkmcnt(0)
	v_add_f32_e32 v76, v68, v71
	v_mov_b32_dpp v51, v50 quad_perm:[2,3,0,1] row_mask:0xf bank_mask:0xf
	v_mov_b32_dpp v53, v52 quad_perm:[2,3,0,1] row_mask:0xf bank_mask:0xf
	v_mov_b32_dpp v55, v54 quad_perm:[2,3,0,1] row_mask:0xf bank_mask:0xf
	v_mov_b32_dpp v57, v56 quad_perm:[2,3,0,1] row_mask:0xf bank_mask:0xf
	v_mov_b32_dpp v60, v59 quad_perm:[2,3,0,1] row_mask:0xf bank_mask:0xf
	v_mov_b32_dpp v62, v61 quad_perm:[2,3,0,1] row_mask:0xf bank_mask:0xf
	v_mov_b32_dpp v64, v63 quad_perm:[2,3,0,1] row_mask:0xf bank_mask:0xf
	v_mov_b32_dpp v66, v65 quad_perm:[2,3,0,1] row_mask:0xf bank_mask:0xf
	ds_bpermute_b32 v68, v179, v58
	ds_bpermute_b32 v67, v179, v67
	ds_bpermute_b32 v71, v179, v69
	ds_bpermute_b32 v69, v179, v70
	ds_bpermute_b32 v73, v179, v72
	ds_bpermute_b32 v72, v179, v74
	ds_bpermute_b32 v70, v179, v75
	ds_bpermute_b32 v58, v179, v76
	s_and_saveexec_b64 s[12:13], s[10:11]
	s_cbranch_execz .LBB0_3848
	s_waitcnt lgkmcnt(1)
	v_cndmask_b32_e64 v74, v70, v73, s[8:9]
	v_cndmask_b32_e64 v73, v73, v71, s[8:9]
	v_cndmask_b32_e64 v71, v71, v68, s[8:9]
	v_cndmask_b32_e64 v68, v68, v141, s[8:9]
	v_add_f32_e32 v50, v50, v51
	v_add_u32_e32 v51, s18, v143
	s_waitcnt lgkmcnt(0)
	v_cndmask_b32_e64 v75, v58, v72, s[8:9]
	v_cndmask_b32_e64 v72, v72, v69, s[8:9]
	v_cndmask_b32_e64 v69, v69, v67, s[8:9]
	v_cndmask_b32_e64 v67, v67, v70, s[8:9]
	v_add_f32_e32 v52, v52, v53
	v_add_u32_e32 v53, 0x10800, v51
	v_add_f32_e32 v50, v50, v68
	v_add_f32_e32 v54, v54, v55
	ds_write_b32 v53, v50
	v_add_f32_e32 v50, v52, v67
	v_add_u32_e32 v52, 0x10820, v51
	v_add_f32_e32 v56, v56, v57
	ds_write_b32 v52, v50
	v_add_f32_e32 v50, v54, v71
	v_add_u32_e32 v52, 0x10808, v51
	v_add_f32_e32 v59, v59, v60
	ds_write_b32 v52, v50
	v_add_f32_e32 v50, v56, v69
	v_add_u32_e32 v52, 0x10828, v51
	v_add_f32_e32 v61, v61, v62
	ds_write_b32 v52, v50
	v_add_f32_e32 v50, v59, v73
	v_add_u32_e32 v52, 0x10810, v51
	v_add_f32_e32 v63, v63, v64
	ds_write_b32 v52, v50
	v_add_f32_e32 v50, v61, v72
	v_add_u32_e32 v52, 0x10830, v51
	v_add_f32_e32 v65, v65, v66
	ds_write_b32 v52, v50
	v_add_f32_e32 v50, v63, v74
	v_add_u32_e32 v52, 0x10818, v51
	ds_write_b32 v52, v50
	v_add_f32_e32 v50, v65, v75
	v_add_u32_e32 v51, 0x10838, v51
	ds_write_b32 v51, v50
